# baseline (speedup 1.0000x reference)
; #define ATT_DMA(t, b) do { \
;         _Pragma("unroll") for (int i_ = 0; i_ < 2; ++i_) glds16(Kg + (size_t)(t) * 64 * ZP + offK[i_], lds + (b) * BUF + (i_ * 8 + wid) * 1024); \
;         _Pragma("unroll") for (int i_ = 0; i_ < 2; ++i_) glds16(Vg + (size_t)(t) * 64 + offV[i_], lds + (b) * BUF + KBYTES + (i_ * 8 + wid) * 1024); } while (0)
; __device__ __forceinline__ void attn_phase(LAS unsigned char* lds, const bf16_t* Z, const bf16_t* VT, bf16_t* Y, const float* subln, float lam, float lam_init, float M0, unsigned* ctr, LAS int* s_unit, int wid_s_) {
;     ...
;         const int U = *s_unit;
;         if (U >= 1024) break;
;         const int h = 7 - (U >> 7), qb = U & 127, q0 = qb * 128, qw = q0 + rg * 32;
;         const float m2 = exp2f(-(float)(h + 1)) * LOG2E;
;         const int W = (int)(150.f / m2) + 1;
;         const int tlo = max(0, q0 - W) >> 6, thi = min(S - 1, q0 + 127 + W) >> 6;
;         const int wlo = max(0, qw - W) >> 6, whi = min(S - 1, qw + 31 + W) >> 6;
;         const bf16_t* Kg = Z + 2048 + h * 128; const bf16_t* Vg = VT + (size_t)h * 128 * S;
;         bf16x8 qf[4];
;         { const bf16_t* qp = Z + (size_t)(qw + rr) * ZP + 1024 + h * 128 + jm * 64 + hh * 8;
; #pragma unroll
;           for (int t4 = 0; t4 < 4; ++t4) qf[t4] = *(const bf16x8*)(qp + t4 * 16); }
;         f32x16 O[4];
; #pragma unroll
;         for (int cb = 0; cb < 4; ++cb)
; #pragma unroll
;             for (int r = 0; r < 16; ++r) O[cb][r] = 0.f;
;         float ls = 0.f;
;     ...
;         const int Tlo = tlo >> 1, Thi = thi >> 1;
;         ATT_DMA(2 * Tlo, 0); ATT_DMA(2 * Tlo + 1, 1);
.LBB0_1294:
	s_or_b64 exec, exec, s[2:3]
	s_waitcnt lgkmcnt(0)
	s_barrier
	ds_read_b32 v0, v97 offset:8
	s_movk_i32 s2, 0x3ff
	s_waitcnt lgkmcnt(0)
	v_cmp_lt_i32_e32 vcc, s2, v0
	v_readfirstlane_b32 s15, v0
	s_mov_b64 s[2:3], -1
	s_cbranch_vccnz .LBB0_1291
	s_bfe_u32 s2, s15, 0x60001
	s_sub_i32 s3, 63, s2
	s_add_i32 s2, s2, 64
	s_bitcmp1_b32 s15, 0
	s_cselect_b32 s2, s3, s2
	s_andn2_b32 s15, s15, 0x7f
	s_or_b32 s15, s15, s2
	s_ashr_i32 s2, s15, 7
	s_sub_i32 s3, 8, s2
	v_cvt_f32_u32_e32 v0, s3
	s_sub_i32 s26, 7, s2
	s_lshl_b32 s2, s15, 7
	s_and_b32 s16, s2, 0x3f80
	s_mov_b32 s2, 0x42fc0000
	v_cmp_lt_f32_e32 vcc, s2, v0
	v_mov_b32_e32 v1, 0x42800000
	s_add_i32 s40, s16, s25
	v_cndmask_b32_e32 v1, 0, v1, vcc
	v_sub_f32_e32 v0, v1, v0
	v_exp_f32_e32 v0, v0
	s_and_b64 s[2:3], vcc, exec
	s_cselect_b32 s2, 0xffffffc0, 0
	s_mov_b32 s15, 0x42fc0000
	v_ldexp_f32 v0, v0, s2
	v_mul_f32_e32 v171, 0x3fb8aa3b, v0
	v_div_scale_f32 v0, s[2:3], v171, v171, s15
	v_rcp_f32_e32 v1, v0
	s_lshl_b32 s41, s26, 7
	s_mov_b32 m0, s37
	v_mov_b32_e32 v15, 0
	v_fma_f32 v2, -v0, v1, 1.0
	v_fmac_f32_e32 v1, v2, v1
	v_div_scale_f32 v2, vcc, s15, v171, s15
	v_mul_f32_e32 v3, v2, v1
	v_fma_f32 v4, -v0, v3, v2
	v_fmac_f32_e32 v3, v4, v1
	v_fma_f32 v0, -v0, v3, v2
	v_div_fmas_f32 v0, v0, v1, v3
	v_div_fixup_f32 v0, v0, v171, s15
	v_cvt_i32_f32_e32 v0, v0
	v_or_b32_e32 v2, s40, v203
	s_mov_b32 s15, s27
	v_mov_b32_e32 v14, 0
	v_readfirstlane_b32 s17, v0
	s_add_i32 s17, s17, 1
	s_add_i32 s2, s17, s16
	v_mov_b64_e32 v[0:1], s[78:79]
	s_add_i32 s51, s2, 0x7f
	s_lshl_b64 s[2:3], s[26:27], 22
	v_mad_i64_i32 v[0:1], s[48:49], v2, s33, v[0:1]
	s_lshl_b32 s26, s26, 8
	s_sub_i32 s50, s16, s17
	v_lshl_add_u64 v[0:1], v[0:1], 0, s[26:27]
	v_lshl_add_u64 v[0:1], v[0:1], 0, s[14:15]
	s_max_i32 s15, s50, 0
	s_add_u32 s50, s22, s26
	s_addc_u32 s78, s23, 0
	s_lshr_b32 s15, s15, 7
	s_lshl_b32 s26, s15, 1
	s_mul_i32 s86, s15, 0x140000
	s_mul_hi_u32 s49, s26, 0xa0000
	s_add_u32 s48, s50, s86
	v_lshl_add_u64 v[0:1], v[0:1], 0, v[96:97]
	s_addc_u32 s49, s78, s49
	flat_load_dwordx4 v[98:101], v[0:1] offset:2048
	flat_load_dwordx4 v[102:105], v[0:1] offset:2080
	flat_load_dwordx4 v[106:109], v[0:1] offset:2112
	flat_load_dwordx4 v[110:113], v[0:1] offset:2144
	v_lshl_add_u64 v[0:1], s[48:49], 0, v[168:169]
	global_load_lds_dwordx4 v[0:1], off
	v_lshl_add_u64 v[0:1], s[48:49], 0, v[166:167]
	s_add_i32 m0, s37, 0x2000
	v_readlane_b32 s48, v255, 52
	v_readlane_b32 s49, v255, 53
	s_add_u32 s48, s48, s2
	s_addc_u32 s49, s49, s3
	s_lshl_b32 s87, s15, 8
	s_add_u32 s48, s48, s87
	s_addc_u32 s49, s49, 0
	global_load_lds_dwordx4 v[0:1], off
	v_lshl_add_u64 v[0:1], v[156:157], 1, s[48:49]
	s_add_i32 m0, s37, 0x4000
	v_lshl_add_u64 v[2:3], v[158:159], 1, s[48:49]
	s_or_b32 s48, s26, 1
	global_load_lds_dwordx4 v[0:1], off
	s_add_i32 m0, s37, 0x6000
	s_min_i32 s51, s51, 0x3fff
	s_mul_hi_u32 s49, s48, 0xa0000
	s_mul_i32 s48, s48, 0xa0000
	s_add_u32 s48, s50, s48
	s_addc_u32 s49, s78, s49
	global_load_lds_dwordx4 v[2:3], off
	v_lshl_add_u64 v[4:5], s[48:49], 0, v[168:169]
	s_add_i32 m0, s37, 0x8000
	v_lshl_add_u64 v[0:1], v[0:1], 0, s[42:43]
	global_load_lds_dwordx4 v[4:5], off
	v_lshl_add_u64 v[4:5], s[48:49], 0, v[166:167]
	s_add_i32 m0, s37, 0xa000
	s_ashr_i32 s48, s51, 7
	global_load_lds_dwordx4 v[4:5], off
	s_add_i32 m0, s37, 0xc000
	v_mov_b32_e32 v13, 0
	global_load_lds_dwordx4 v[0:1], off
	v_lshl_add_u64 v[0:1], v[2:3], 0, s[42:43]
	s_add_i32 m0, s37, 0xe000
	s_cmp_gt_i32 s15, s48
	global_load_lds_dwordx4 v[0:1], off
	v_mov_b32_e32 v12, 0
	v_mov_b32_e32 v11, 0
	v_mov_b32_e32 v10, 0
	v_mov_b32_e32 v9, 0
	v_mov_b32_e32 v8, 0
	v_mov_b32_e32 v7, 0
	v_mov_b32_e32 v6, 0
	v_mov_b32_e32 v5, 0
	v_mov_b32_e32 v4, 0
	v_mov_b32_e32 v3, 0
	v_mov_b32_e32 v2, 0
	v_mov_b32_e32 v1, 0
	v_mov_b32_e32 v0, 0
	v_mov_b32_e32 v31, 0
	v_mov_b32_e32 v30, 0
	v_mov_b32_e32 v29, 0
	v_mov_b32_e32 v28, 0
	v_mov_b32_e32 v27, 0
	v_mov_b32_e32 v26, 0
	v_mov_b32_e32 v25, 0
	v_mov_b32_e32 v24, 0
	v_mov_b32_e32 v23, 0
	v_mov_b32_e32 v22, 0
	v_mov_b32_e32 v21, 0
	v_mov_b32_e32 v20, 0
	v_mov_b32_e32 v19, 0
	v_mov_b32_e32 v18, 0
	v_mov_b32_e32 v17, 0
	v_mov_b32_e32 v16, 0
	v_mov_b32_e32 v63, 0
	v_mov_b32_e32 v62, 0
	v_mov_b32_e32 v61, 0
	v_mov_b32_e32 v60, 0
	v_mov_b32_e32 v59, 0
	v_mov_b32_e32 v58, 0
	v_mov_b32_e32 v57, 0
	v_mov_b32_e32 v56, 0
	v_mov_b32_e32 v55, 0
	v_mov_b32_e32 v54, 0
	v_mov_b32_e32 v53, 0
	v_mov_b32_e32 v52, 0
	v_mov_b32_e32 v51, 0
	v_mov_b32_e32 v50, 0
	v_mov_b32_e32 v49, 0
	v_mov_b32_e32 v48, 0
	v_mov_b32_e32 v47, 0
	v_mov_b32_e32 v46, 0
	v_mov_b32_e32 v45, 0
	v_mov_b32_e32 v44, 0
	v_mov_b32_e32 v43, 0
	v_mov_b32_e32 v42, 0
	v_mov_b32_e32 v41, 0
	v_mov_b32_e32 v40, 0
	v_mov_b32_e32 v39, 0
	v_mov_b32_e32 v38, 0
	v_mov_b32_e32 v37, 0
	v_mov_b32_e32 v36, 0
	v_mov_b32_e32 v35, 0
	v_mov_b32_e32 v34, 0
	v_mov_b32_e32 v33, 0
	v_mov_b32_e32 v32, 0
	v_mov_b32_e32 v197, 0
	s_cbranch_scc1 .LBB0_1315
	s_sub_i32 s50, s40, s17
	s_max_i32 s51, s50, 0
	s_or_b32 s50, s40, 31
	s_add_i32 s17, s17, s50
	s_min_i32 s17, s17, 0x3fff
	s_lshr_b32 s51, s51, 6
	s_ashr_i32 s84, s17, 6
	s_lshl_b32 s85, s15, 7
	s_add_u32 s2, s87, s2
	s_addc_u32 s3, 0, s3
	v_lshl_add_u64 v[176:177], s[2:3], 0, v[162:163]
	v_lshl_add_u64 v[178:179], s[2:3], 0, v[164:165]
	s_lshl_b32 s2, s41, 1
	v_add_u32_e32 v0, s16, v240
	s_mul_hi_u32 s3, s15, 0x140000
	s_add_u32 s2, s2, s86
	v_mov_b32_e32 v32, v97
	v_mov_b32_e32 v33, v97
	v_mov_b32_e32 v46, v97
	v_mov_b32_e32 v47, v97
	v_xor_b32_e32 v172, 0x80000000, v171
	v_subrev_u32_e32 v193, s85, v0
	s_addc_u32 s3, 0, s3
	v_mov_b32_e32 v34, v97
	v_mov_b32_e32 v35, v97
	v_mov_b32_e32 v36, v97
	v_mov_b32_e32 v37, v97
	v_mov_b32_e32 v38, v97
	v_mov_b32_e32 v39, v97
	v_mov_b32_e32 v40, v97
	v_mov_b32_e32 v41, v97
	v_mov_b32_e32 v42, v97
	v_mov_b32_e32 v43, v97
	v_mov_b32_e32 v44, v97
	v_mov_b32_e32 v45, v97
	v_mov_b64_e32 v[62:63], v[46:47]
	v_mov_b64_e32 v[16:17], v[32:33]
	v_mov_b64_e32 v[0:1], v[32:33]
	s_mov_b32 s49, 0
	v_mov_b32_e32 v174, v172
	v_mov_b32_e32 v175, v172
	v_lshl_add_u64 v[180:181], s[2:3], 0, v[166:167]
	v_lshl_add_u64 v[182:183], s[2:3], 0, v[168:169]
	v_mov_b32_e32 v197, 0
	v_mov_b64_e32 v[60:61], v[44:45]
	v_mov_b64_e32 v[58:59], v[42:43]
	v_mov_b64_e32 v[56:57], v[40:41]
	v_mov_b64_e32 v[54:55], v[38:39]
	v_mov_b64_e32 v[52:53], v[36:37]
	v_mov_b64_e32 v[50:51], v[34:35]
	v_mov_b64_e32 v[48:49], v[32:33]
	v_mov_b64_e32 v[18:19], v[34:35]
	v_mov_b64_e32 v[20:21], v[36:37]
	v_mov_b64_e32 v[22:23], v[38:39]
	v_mov_b64_e32 v[24:25], v[40:41]
	v_mov_b64_e32 v[26:27], v[42:43]
	v_mov_b64_e32 v[28:29], v[44:45]
	v_mov_b64_e32 v[30:31], v[46:47]
	v_mov_b64_e32 v[2:3], v[34:35]
	v_mov_b64_e32 v[4:5], v[36:37]
	v_mov_b64_e32 v[6:7], v[38:39]
	v_mov_b64_e32 v[8:9], v[40:41]
	v_mov_b64_e32 v[10:11], v[42:43]
	v_mov_b64_e32 v[12:13], v[44:45]
	v_mov_b64_e32 v[14:15], v[46:47]
	s_waitcnt vmcnt(0)
	s_branch .LBB0_1299
